# LN1 phase row loop rewritten: hoisted gain/bias, next-row prefetch, DPP wave sums, cvt_pk_bf16
# baseline (speedup 1.0000x reference)
.LBB0_42:
	v_mov_b32_e32 v0, v220
	v_readlane_b32 s0, v249, 0
	s_nop 0
	v_ashrrev_i32_e32 v1, 6, v0
	v_lshl_add_u32 v12, s0, 2, v1
	s_movk_i32 s0, 0x4200
	v_cmp_gt_i32_e32 vcc, s0, v12
	s_and_saveexec_b64 s[0:1], vcc
	v_readlane_b32 s12, v249, 9
	s_mov_b32 s13, 0x800000
	s_movk_i32 s14, 0x41ff
	s_cbranch_execz .LBB0_45
	v_readlane_b32 s16, v249, 30
	v_readlane_b32 s17, v249, 31
	s_waitcnt lgkmcnt(0)
	s_load_dwordx4 s[8:11], s[16:17], 0x80
	v_readlane_b32 s2, v249, 39
	v_readlane_b32 s3, v249, 40
	s_lshl_b64 s[2:3], s[2:3], 2
	v_lshlrev_b32_e32 v0, 4, v0
	s_waitcnt lgkmcnt(0)
	s_add_u32 s8, s8, s2
	s_addc_u32 s9, s9, s3
	v_and_b32_e32 v2, 0x3f0, v0
	s_add_u32 s2, s10, s2
	v_lshlrev_b32_e32 v0, 2, v2
	v_mov_b32_e32 v1, v80
	s_addc_u32 s3, s11, s3
	v_lshl_add_u64 v[14:15], s[8:9], 0, v[0:1]
	v_lshl_add_u64 v[16:17], s[2:3], 0, v[0:1]
	v_lshlrev_b32_e32 v0, 1, v2
	v_and_b32_e32 v2, 64, v229
	v_add_u32_e32 v2, 64, v2
	v_xor_b32_e32 v3, 32, v229
	v_cmp_lt_i32_e32 vcc, v3, v2
	s_load_dwordx2 s[2:3], s[16:17], 0x178
	s_waitcnt lgkmcnt(0)
	v_lshl_add_u64 v[18:19], s[2:3], 0, v[0:1]
	v_cndmask_b32_e32 v3, v229, v3, vcc
	v_lshlrev_b32_e32 v24, 2, v3
	v_xor_b32_e32 v3, 16, v229
	v_cmp_lt_i32_e32 vcc, v3, v2
	s_load_dwordx2 s[2:3], s[16:17], 0x140
	s_waitcnt lgkmcnt(0)
	v_lshl_add_u64 v[20:21], s[2:3], 0, v[0:1]
	v_cndmask_b32_e32 v3, v229, v3, vcc
	v_lshlrev_b32_e32 v25, 2, v3
	v_xor_b32_e32 v3, 8, v229
	v_cmp_lt_i32_e32 vcc, v3, v2
	s_mov_b64 s[2:3], 0
	s_nop 0
	v_cndmask_b32_e32 v3, v229, v3, vcc
	v_lshlrev_b32_e32 v26, 2, v3
	v_xor_b32_e32 v3, 4, v229
	v_cmp_lt_i32_e32 vcc, v3, v2
	s_nop 1
	v_cndmask_b32_e32 v3, v229, v3, vcc
	v_lshlrev_b32_e32 v27, 2, v3
	v_xor_b32_e32 v3, 2, v229
	v_cmp_lt_i32_e32 vcc, v3, v2
	s_nop 1
	v_cndmask_b32_e32 v3, v229, v3, vcc
	v_lshlrev_b32_e32 v28, 2, v3
	v_xor_b32_e32 v3, 1, v229
	v_cmp_lt_i32_e32 vcc, v3, v2
	s_nop 1
	v_cndmask_b32_e32 v2, v229, v3, vcc
	v_lshlrev_b32_e32 v29, 2, v2
	global_load_dwordx4 v[120:123], v[14:15], off
	global_load_dwordx4 v[124:127], v[14:15], off offset:16
	global_load_dwordx4 v[128:131], v[14:15], off offset:32
	global_load_dwordx4 v[132:135], v[14:15], off offset:48
	global_load_dwordx4 v[136:139], v[16:17], off
	global_load_dwordx4 v[140:143], v[16:17], off offset:16
	global_load_dwordx4 v[144:147], v[16:17], off offset:32
	global_load_dwordx4 v[148:151], v[16:17], off offset:48
	v_mov_b32_e32 v87, 0
	v_mov_b32_e32 v89, 0
	v_lshlrev_b32_e32 v86, 11, v12
	v_lshl_add_u64 v[0:1], v[18:19], 0, v[86:87]
	global_load_dwordx4 v[8:11], v[0:1], off
	global_load_dwordx4 v[30:33], v[0:1], off offset:16
	s_waitcnt vmcnt(0)
.Lln1_row:
	v_lshlrev_b32_e32 v50, 16, v8
	v_and_b32_e32 v51, 0xffff0000, v8
	v_lshlrev_b32_e32 v52, 16, v9
	v_and_b32_e32 v53, 0xffff0000, v9
	v_lshlrev_b32_e32 v54, 16, v10
	v_and_b32_e32 v55, 0xffff0000, v10
	v_lshlrev_b32_e32 v56, 16, v11
	v_and_b32_e32 v57, 0xffff0000, v11
	v_lshlrev_b32_e32 v58, 16, v30
	v_and_b32_e32 v59, 0xffff0000, v30
	v_lshlrev_b32_e32 v60, 16, v31
	v_and_b32_e32 v61, 0xffff0000, v31
	v_lshlrev_b32_e32 v62, 16, v32
	v_and_b32_e32 v63, 0xffff0000, v32
	v_lshlrev_b32_e32 v64, 16, v33
	v_and_b32_e32 v65, 0xffff0000, v33
	v_add_u32_e32 v84, s12, v12
	v_min_i32_e32 v85, s14, v84
	v_lshlrev_b32_e32 v86, 11, v85
	v_lshlrev_b32_e32 v88, 11, v12
	v_lshl_add_u64 v[0:1], v[18:19], 0, v[86:87]
	global_load_dwordx4 v[8:11], v[0:1], off
	global_load_dwordx4 v[30:33], v[0:1], off offset:16
	v_lshl_add_u64 v[22:23], v[20:21], 0, v[88:89]
	v_pk_add_f32 v[66:67], v[50:51], v[52:53]
	v_pk_add_f32 v[68:69], v[54:55], v[56:57]
	v_pk_add_f32 v[70:71], v[58:59], v[60:61]
	v_pk_add_f32 v[72:73], v[62:63], v[64:65]
	v_pk_add_f32 v[66:67], v[66:67], v[68:69]
	v_pk_add_f32 v[70:71], v[70:71], v[72:73]
	v_pk_add_f32 v[66:67], v[66:67], v[70:71]
	v_add_f32_e32 v66, v66, v67
	s_nop 1
	v_add_f32_dpp v66, v66, v66 quad_perm:[1,0,3,2] row_mask:0xf bank_mask:0xf
	s_nop 1
	v_add_f32_dpp v66, v66, v66 quad_perm:[2,3,0,1] row_mask:0xf bank_mask:0xf
	s_nop 1
	v_add_f32_dpp v66, v66, v66 row_half_mirror row_mask:0xf bank_mask:0xf
	s_nop 1
	v_add_f32_dpp v66, v66, v66 row_mirror row_mask:0xf bank_mask:0xf
	s_nop 1
	v_add_f32_dpp v66, v66, v66 row_bcast:15 row_mask:0xa bank_mask:0xf
	s_nop 1
	v_add_f32_dpp v66, v66, v66 row_bcast:31 row_mask:0xc bank_mask:0xf
	s_nop 1
	v_readlane_b32 s8, v66, 63
	s_nop 1
	v_mov_b32_e32 v66, s8
	v_mul_f32_e32 v66, 0x3a800000, v66
	v_pk_add_f32 v[50:51], v[50:51], v[66:67] op_sel_hi:[1,0] neg_lo:[0,1] neg_hi:[0,1]
	v_pk_add_f32 v[52:53], v[52:53], v[66:67] op_sel_hi:[1,0] neg_lo:[0,1] neg_hi:[0,1]
	v_pk_add_f32 v[54:55], v[54:55], v[66:67] op_sel_hi:[1,0] neg_lo:[0,1] neg_hi:[0,1]
	v_pk_add_f32 v[56:57], v[56:57], v[66:67] op_sel_hi:[1,0] neg_lo:[0,1] neg_hi:[0,1]
	v_pk_add_f32 v[58:59], v[58:59], v[66:67] op_sel_hi:[1,0] neg_lo:[0,1] neg_hi:[0,1]
	v_pk_add_f32 v[60:61], v[60:61], v[66:67] op_sel_hi:[1,0] neg_lo:[0,1] neg_hi:[0,1]
	v_pk_add_f32 v[62:63], v[62:63], v[66:67] op_sel_hi:[1,0] neg_lo:[0,1] neg_hi:[0,1]
	v_pk_add_f32 v[64:65], v[64:65], v[66:67] op_sel_hi:[1,0] neg_lo:[0,1] neg_hi:[0,1]
	v_pk_mul_f32 v[68:69], v[50:51], v[50:51]
	v_pk_fma_f32 v[68:69], v[52:53], v[52:53], v[68:69]
	v_pk_fma_f32 v[68:69], v[54:55], v[54:55], v[68:69]
	v_pk_fma_f32 v[68:69], v[56:57], v[56:57], v[68:69]
	v_pk_fma_f32 v[68:69], v[58:59], v[58:59], v[68:69]
	v_pk_fma_f32 v[68:69], v[60:61], v[60:61], v[68:69]
	v_pk_fma_f32 v[68:69], v[62:63], v[62:63], v[68:69]
	v_pk_fma_f32 v[68:69], v[64:65], v[64:65], v[68:69]
	v_add_f32_e32 v68, v68, v69
	s_nop 1
	v_add_f32_dpp v68, v68, v68 quad_perm:[1,0,3,2] row_mask:0xf bank_mask:0xf
	s_nop 1
	v_add_f32_dpp v68, v68, v68 quad_perm:[2,3,0,1] row_mask:0xf bank_mask:0xf
	s_nop 1
	v_add_f32_dpp v68, v68, v68 row_half_mirror row_mask:0xf bank_mask:0xf
	s_nop 1
	v_add_f32_dpp v68, v68, v68 row_mirror row_mask:0xf bank_mask:0xf
	s_nop 1
	v_add_f32_dpp v68, v68, v68 row_bcast:15 row_mask:0xa bank_mask:0xf
	s_nop 1
	v_add_f32_dpp v68, v68, v68 row_bcast:31 row_mask:0xc bank_mask:0xf
	s_nop 1
	v_readlane_b32 s8, v68, 63
	s_nop 1
	v_mov_b32_e32 v68, s8
	v_fmamk_f32 v68, v68, 0x3a800000, v221
	v_mul_f32_e32 v69, 0x4b800000, v68
	v_cmp_gt_f32_e32 vcc, s13, v68
	s_nop 1
	v_cndmask_b32_e32 v68, v68, v69, vcc
	v_rsq_f32_e32 v68, v68
	s_nop 0
	v_mul_f32_e32 v69, 0x45800000, v68
	v_cndmask_b32_e32 v70, v68, v69, vcc
	v_pk_mul_f32 v[50:51], v[50:51], v[70:71] op_sel_hi:[1,0]
	v_pk_mul_f32 v[52:53], v[52:53], v[70:71] op_sel_hi:[1,0]
	v_pk_mul_f32 v[54:55], v[54:55], v[70:71] op_sel_hi:[1,0]
	v_pk_mul_f32 v[56:57], v[56:57], v[70:71] op_sel_hi:[1,0]
	v_pk_mul_f32 v[58:59], v[58:59], v[70:71] op_sel_hi:[1,0]
	v_pk_mul_f32 v[60:61], v[60:61], v[70:71] op_sel_hi:[1,0]
	v_pk_mul_f32 v[62:63], v[62:63], v[70:71] op_sel_hi:[1,0]
	v_pk_mul_f32 v[64:65], v[64:65], v[70:71] op_sel_hi:[1,0]
	v_pk_fma_f32 v[50:51], v[120:121], v[50:51], v[136:137]
	v_pk_fma_f32 v[52:53], v[122:123], v[52:53], v[138:139]
	v_pk_fma_f32 v[54:55], v[124:125], v[54:55], v[140:141]
	v_pk_fma_f32 v[56:57], v[126:127], v[56:57], v[142:143]
	v_pk_fma_f32 v[58:59], v[128:129], v[58:59], v[144:145]
	v_pk_fma_f32 v[60:61], v[130:131], v[60:61], v[146:147]
	v_pk_fma_f32 v[62:63], v[132:133], v[62:63], v[148:149]
	v_pk_fma_f32 v[64:65], v[134:135], v[64:65], v[150:151]
	v_cvt_pk_bf16_f32 v72, v50, v51
	v_cvt_pk_bf16_f32 v73, v52, v53
	v_cvt_pk_bf16_f32 v74, v54, v55
	v_cvt_pk_bf16_f32 v75, v56, v57
	v_cvt_pk_bf16_f32 v76, v58, v59
	v_cvt_pk_bf16_f32 v77, v60, v61
	v_cvt_pk_bf16_f32 v78, v62, v63
	v_cvt_pk_bf16_f32 v79, v64, v65
	s_waitcnt vmcnt(0)
	global_store_dwordx4 v[22:23], v[72:75], off
	global_store_dwordx4 v[22:23], v[76:79], off offset:16
	v_mov_b32_e32 v12, v84
	v_cmp_lt_i32_e32 vcc, s14, v12
	s_or_b64 s[2:3], vcc, s[2:3]
	s_andn2_b64 exec, exec, s[2:3]
	s_cbranch_execnz .Lln1_row
